# P3 attention unit prologue: second K/V block's staging loads issued with the first block's and Q loads
# speedup vs baseline: 1.0047x; 1.0047x over previous
.LBB0_432:
	s_ashr_i32 s69, s59, 6
	s_lshl_b32 s3, s59, 8
	s_lshl_b32 s2, s69, 11
	s_and_b32 s3, s3, 0x700
	s_bfe_u32 s6, s59, 0x10005
	s_or_b32 s26, s2, s3
	s_lshl_b32 s3, s59, 4
	s_ashr_i32 s27, s26, 31
	s_lshl_b32 s2, s6, 9
	s_and_b32 s3, s3, 0x180
	s_lshl_b32 s68, s6, 8
	s_or_b32 s63, s2, s3
	s_lshl_b64 s[2:3], s[26:27], 11
	s_add_u32 s2, s22, s2
	s_addc_u32 s3, s23, s3
	s_lshl_b32 s7, s63, 1
	s_add_u32 s8, s2, s7
	s_mul_i32 s2, s69, 0x1200
	s_addc_u32 s9, s3, 0
	s_mul_hi_i32 s3, s69, 0x1200
	s_or_b32 s2, s2, s6
	v_mov_b32_e32 v68, v208
	s_lshl_b64 s[6:7], s[2:3], 8
	s_add_u32 s2, s24, s6
	v_ashrrev_i32_e32 v16, 4, v68
	v_lshlrev_b32_e32 v22, 3, v68
	v_add_u32_e32 v18, 32, v16
	s_addc_u32 s3, s25, s7
	v_and_b32_e32 v0, 0x78, v22
	v_ashrrev_i32_e32 v17, 31, v16
	v_ashrrev_i32_e32 v19, 31, v18
	s_add_u32 s6, s1, s6
	v_lshlrev_b32_e32 v23, 1, v0
	v_lshlrev_b64 v[48:49], 9, v[16:17]
	v_lshlrev_b64 v[8:9], 9, v[18:19]
	s_addc_u32 s7, s54, s7
	v_or_b32_e32 v50, v48, v23
	v_mov_b32_e32 v51, v49
	v_or_b32_e32 v8, v8, v23
	v_ashrrev_i32_e32 v155, 6, v68
	v_lshl_add_u64 v[0:1], s[6:7], 0, v[50:51]
	v_lshl_add_u64 v[4:5], s[6:7], 0, v[8:9]
	v_lshl_add_u64 v[10:11], s[2:3], 0, v[50:51]
	v_lshl_add_u64 v[12:13], s[2:3], 0, v[8:9]
	v_and_b32_e32 v154, 31, v68
	v_lshlrev_b32_e32 v130, 5, v155
	v_lshl_add_u64 v[218:219], v[0:1], 0, s[16:17]
	v_lshl_add_u64 v[222:223], v[4:5], 0, s[16:17]
	v_lshl_add_u64 v[226:227], v[10:11], 0, s[16:17]
	v_lshl_add_u64 v[230:231], v[12:13], 0, s[16:17]
	global_load_dwordx4 v[0:3], v[0:1], off
	s_nop 0
	global_load_dwordx4 v[4:7], v[4:5], off
	s_nop 0
	global_load_dwordx4 v[8:11], v[10:11], off
	s_nop 0
	global_load_dwordx4 v[12:15], v[12:13], off
	v_or_b32_e32 v20, v130, v154
	v_ashrrev_i32_e32 v21, 31, v20
	v_bfe_u32 v153, v68, 5, 1
	v_lshlrev_b64 v[20:21], 11, v[20:21]
	v_lshl_add_u64 v[20:21], s[8:9], 0, v[20:21]
	v_lshlrev_b32_e32 v128, 4, v153
	v_lshl_add_u64 v[20:21], v[20:21], 0, v[128:129]
	global_load_dwordx4 v[124:127], v[20:21], off
	global_load_dwordx4 v[120:123], v[20:21], off offset:32
	global_load_dwordx4 v[112:115], v[20:21], off offset:64
	global_load_dwordx4 v[116:119], v[20:21], off offset:96
	global_load_dwordx4 v[108:111], v[20:21], off offset:128
	global_load_dwordx4 v[104:107], v[20:21], off offset:160
	global_load_dwordx4 v[100:103], v[20:21], off offset:192
	global_load_dwordx4 v[96:99], v[20:21], off offset:224
	global_load_dwordx4 v[218:221], v[218:219], off
	global_load_dwordx4 v[222:225], v[222:223], off
	global_load_dwordx4 v[226:229], v[226:227], off
	global_load_dwordx4 v[230:233], v[230:231], off
	v_and_b32_e32 v19, 0xfffff0, v16
	v_lshlrev_b32_e32 v24, 1, v16
	v_lshrrev_b32_e32 v25, 1, v16
	v_and_b32_e32 v26, 3, v16
	v_and_or_b32 v19, v16, 8, v19
	v_and_or_b32 v24, v16, 4, v26
	v_and_b32_e32 v25, 0xfffff0, v18
	v_and_or_b32 v25, v18, 8, v25
	v_lshlrev_b32_e32 v26, 1, v18
	v_and_b32_e32 v17, 0x70, v68
	v_bfe_u32 v22, v22, 5, 2
	v_lshlrev_b32_e32 v16, 8, v16
	v_lshlrev_b32_e32 v18, 8, v18
	v_lshrrev_b32_e32 v19, 1, v19
	v_lshlrev_b32_e32 v156, 4, v68
	v_bitop3_b32 v162, v23, v16, v17 bitop3:0xde
	v_bitop3_b32 v163, v23, v18, v17 bitop3:0xde
	v_or_b32_e32 v16, v19, v22
	v_lshrrev_b32_e32 v17, 1, v25
	v_lshlrev_b32_e32 v24, 6, v24
	v_and_b32_e32 v27, 48, v23
	v_lshlrev_b32_e32 v16, 9, v16
	v_or_b32_e32 v17, v17, v22
	v_lshlrev_b32_e32 v60, 8, v154
	v_and_b32_e32 v61, 0x70, v156
	v_or3_b32 v164, v16, v24, v27
	v_lshlrev_b32_e32 v16, 9, v17
	v_bitop3_b32 v166, v128, v60, v61 bitop3:0xde
	v_or3_b32 v165, v16, v24, v27
	s_waitcnt vmcnt(0)
	v_and_b32_e32 v62, 0x3fffffc0, v68
	v_and_b32_e32 v157, 63, v68
	v_lshlrev_b32_e32 v63, 1, v68
	v_lshl_add_u32 v131, v62, 2, v150
	v_lshlrev_b32_e32 v62, 3, v157
	v_lshl_or_b32 v158, v154, 2, v131
	s_waitcnt vmcnt(11)
	ds_write_b128 v164, v[0:3]
	s_waitcnt vmcnt(10)
	ds_write_b128 v165, v[4:7]
	s_waitcnt vmcnt(9)
	ds_write_b128 v162, v[8:11] offset:32768
	s_waitcnt vmcnt(8)
	ds_write_b128 v163, v[12:15] offset:32768
	s_waitcnt lgkmcnt(0)
	s_barrier
	ds_read_b128 v[0:3], v166 offset:32768
	ds_read_b128 v[4:7], v166 offset:40960
	s_waitcnt vmcnt(7) lgkmcnt(1)
	v_mfma_f32_32x32x16_bf16 v[32:47], v[0:3], v[124:127], 0
	v_or_b32_e32 v0, 32, v128
	v_bitop3_b32 v167, v0, v60, v61 bitop3:0xde
	v_mov_b32_e32 v159, 0
	s_waitcnt lgkmcnt(0)
	v_mfma_f32_32x32x16_bf16 v[16:31], v[4:7], v[124:127], 0
	ds_read_b128 v[0:3], v167 offset:32768
	ds_read_b128 v[4:7], v167 offset:40960
	s_waitcnt vmcnt(6) lgkmcnt(1)
	v_mfma_f32_32x32x16_bf16 v[32:47], v[0:3], v[120:123], v[32:47]
	v_or_b32_e32 v0, 64, v128
	v_bitop3_b32 v168, v0, v60, v61 bitop3:0xde
	s_waitcnt lgkmcnt(0)
	v_mfma_f32_32x32x16_bf16 v[16:31], v[4:7], v[120:123], v[16:31]
	ds_read_b128 v[0:3], v168 offset:32768
	ds_read_b128 v[4:7], v168 offset:40960
	s_waitcnt vmcnt(5) lgkmcnt(1)
	v_mfma_f32_32x32x16_bf16 v[32:47], v[0:3], v[112:115], v[32:47]
	v_or_b32_e32 v0, 0x60, v128
	v_bitop3_b32 v169, v0, v60, v61 bitop3:0xde
	s_waitcnt lgkmcnt(0)
	v_mfma_f32_32x32x16_bf16 v[16:31], v[4:7], v[112:115], v[16:31]
	ds_read_b128 v[0:3], v169 offset:32768
	ds_read_b128 v[4:7], v169 offset:40960
	s_waitcnt vmcnt(4) lgkmcnt(1)
	v_mfma_f32_32x32x16_bf16 v[32:47], v[0:3], v[116:119], v[32:47]
	v_or_b32_e32 v0, 0x80, v128
	v_bitop3_b32 v170, v0, v60, v61 bitop3:0xde
	s_waitcnt lgkmcnt(0)
	v_mfma_f32_32x32x16_bf16 v[16:31], v[4:7], v[116:119], v[16:31]
	ds_read_b128 v[0:3], v170 offset:32768
	ds_read_b128 v[4:7], v170 offset:40960
	s_waitcnt vmcnt(3) lgkmcnt(1)
	v_mfma_f32_32x32x16_bf16 v[32:47], v[0:3], v[108:111], v[32:47]
	v_or_b32_e32 v0, 0xa0, v128
	v_bitop3_b32 v171, v0, v60, v61 bitop3:0xde
	s_waitcnt lgkmcnt(0)
	v_mfma_f32_32x32x16_bf16 v[16:31], v[4:7], v[108:111], v[16:31]
	ds_read_b128 v[0:3], v171 offset:32768
	ds_read_b128 v[4:7], v171 offset:40960
	s_waitcnt vmcnt(2) lgkmcnt(1)
	v_mfma_f32_32x32x16_bf16 v[32:47], v[0:3], v[104:107], v[32:47]
	v_or_b32_e32 v0, 0xc0, v128
	v_bitop3_b32 v172, v0, v60, v61 bitop3:0xde
	ds_read_b128 v[52:55], v172 offset:32768
	ds_read_b128 v[56:59], v172 offset:40960
	s_waitcnt lgkmcnt(2)
	v_mfma_f32_32x32x16_bf16 v[16:31], v[4:7], v[104:107], v[16:31]
	v_mov_b64_e32 v[0:1], s[36:37]
	v_mov_b64_e32 v[14:15], s[50:51]
	v_mov_b64_e32 v[2:3], s[38:39]
	v_mov_b64_e32 v[4:5], s[40:41]
	v_mov_b64_e32 v[6:7], s[42:43]
	v_mov_b64_e32 v[8:9], s[44:45]
	v_mov_b64_e32 v[10:11], s[46:47]
	s_waitcnt vmcnt(1) lgkmcnt(1)
	v_mfma_f32_32x32x16_bf16 v[32:47], v[52:55], v[100:103], v[32:47]
	v_or_b32_e32 v52, 0xe0, v128
	v_bitop3_b32 v173, v52, v60, v61 bitop3:0xde
	ds_read_b128 v[52:55], v173 offset:32768
	v_lshl_add_u64 v[60:61], v[50:51], 0, s[16:17]
	v_lshl_add_u64 v[50:51], v[50:51], 0, s[18:19]
	v_lshl_add_u64 v[64:65], s[2:3], 0, v[50:51]
	v_mov_b64_e32 v[12:13], s[48:49]
	s_waitcnt lgkmcnt(1)
	v_mfma_f32_32x32x16_bf16 v[16:31], v[56:59], v[100:103], v[16:31]
	v_and_b32_e32 v56, 0xc0, v156
	v_and_b32_e32 v57, 32, v63
	v_and_or_b32 v56, v62, 24, v56
	v_and_b32_e32 v58, 0x100, v62
	v_or3_b32 v161, v56, v57, v58
	ds_read_b128 v[56:59], v173 offset:40960
	v_or_b32_e32 v160, 0x4000, v161
	s_waitcnt vmcnt(0) lgkmcnt(1)
	v_mfma_f32_32x32x16_bf16 v[32:47], v[52:55], v[96:99], v[32:47]
	v_lshl_add_u64 v[54:55], s[2:3], 0, v[60:61]
	v_lshl_add_u64 v[52:53], s[6:7], 0, v[60:61]
	v_lshl_add_u64 v[60:61], s[6:7], 0, v[50:51]
	s_nop 0
	v_cmp_gt_u32_e64 s[6:7], 32, v157
	s_waitcnt lgkmcnt(0)
	v_mfma_f32_32x32x16_bf16 v[16:31], v[56:59], v[96:99], v[16:31]
	s_nop 0
	v_max_f32_e32 v58, v33, v33
	v_max_f32_e32 v59, v32, v32
	v_max_f32_e32 v58, v59, v58
	v_max3_f32 v58, v58, v34, v35
	v_max3_f32 v58, v58, v36, v37
	v_max3_f32 v58, v58, v38, v39
	v_max3_f32 v58, v58, v40, v41
	v_max3_f32 v58, v58, v42, v43
	v_max3_f32 v58, v58, v44, v45
	v_max3_f32 v58, v58, v46, v47
	v_max3_f32 v58, v58, v16, v17
	v_max3_f32 v58, v58, v18, v19
	v_max3_f32 v58, v58, v20, v21
	v_max3_f32 v58, v58, v22, v23
	v_max3_f32 v58, v58, v24, v25
	v_max3_f32 v58, v58, v26, v27
	v_max3_f32 v58, v58, v28, v29
	v_max3_f32 v58, v58, v30, v31
	v_mov_b32_e32 v59, v58
	s_nop 1
	v_permlane32_swap_b32_e32 v58, v59
	v_max_f32_e32 v59, v59, v59
	v_max_f32_e32 v58, v58, v58
	v_max_f32_e32 v58, v58, v59
	v_add_f32_e32 v59, 0x7149f2ca, v58
	v_max_f32_e32 v58, 0xf149f2ca, v58
	v_cmp_ge_f32_e32 vcc, s15, v59
	v_sub_f32_e32 v59, 0xf149f2ca, v58
	v_mul_f32_e32 v59, 0x3e0293ee, v59
	v_exp_f32_e32 v59, v59
	s_cmp_eq_u64 vcc, exec
	s_cselect_b64 vcc, -1, 0
	v_cndmask_b32_e32 v175, v58, v151, vcc
	v_mul_f32_e32 v58, 0xbe0293ee, v175
	v_cndmask_b32_e64 v174, v59, 1.0, vcc
	v_mov_b32_e32 v59, v58
	v_fmac_f32_e32 v59, 0x3e0293ee, v47
	v_fmamk_f32 v32, v32, 0x3e0293ee, v58
	v_fmamk_f32 v33, v33, 0x3e0293ee, v58
	v_fmamk_f32 v34, v34, 0x3e0293ee, v58
	v_fmamk_f32 v35, v35, 0x3e0293ee, v58
	v_fmamk_f32 v36, v36, 0x3e0293ee, v58
	v_fmamk_f32 v37, v37, 0x3e0293ee, v58
	v_fmamk_f32 v38, v38, 0x3e0293ee, v58
	v_fmamk_f32 v39, v39, 0x3e0293ee, v58
	v_fmamk_f32 v40, v40, 0x3e0293ee, v58
	v_fmamk_f32 v41, v41, 0x3e0293ee, v58
	v_fmamk_f32 v42, v42, 0x3e0293ee, v58
	v_fmamk_f32 v43, v43, 0x3e0293ee, v58
	v_fmamk_f32 v44, v44, 0x3e0293ee, v58
	v_fmamk_f32 v45, v45, 0x3e0293ee, v58
	v_fmamk_f32 v46, v46, 0x3e0293ee, v58
	v_pk_fma_f32 v[140:141], v[18:19], s[14:15], v[58:59] op_sel_hi:[1,0,0]
	v_and_b32_e32 v18, 15, v68
	v_pk_fma_f32 v[142:143], v[16:17], s[14:15], v[58:59] op_sel_hi:[1,0,0]
	v_exp_f32_e32 v190, v32
	v_exp_f32_e32 v191, v33
	v_exp_f32_e32 v192, v34
	v_exp_f32_e32 v193, v35
	v_exp_f32_e32 v194, v36
	v_exp_f32_e32 v196, v37
	v_exp_f32_e32 v195, v38
	v_exp_f32_e32 v197, v39
	v_exp_f32_e32 v182, v40
	v_exp_f32_e32 v183, v41
	v_exp_f32_e32 v184, v42
	v_exp_f32_e32 v186, v43
	v_exp_f32_e32 v185, v44
	v_exp_f32_e32 v187, v45
	v_exp_f32_e32 v188, v46
	v_exp_f32_e32 v189, v59
	v_mad_i64_i32 v[16:17], s[2:3], s69, v152, v[48:49]
	v_lshlrev_b32_e32 v18, 4, v18
	s_waitcnt vmcnt(0)
	v_or3_b32 v16, v16, s68, v18
	v_pk_fma_f32 v[144:145], v[30:31], s[14:15], v[58:59] op_sel_hi:[1,0,0]
	v_pk_fma_f32 v[146:147], v[28:29], s[14:15], v[58:59] op_sel_hi:[1,0,0]
	v_pk_fma_f32 v[148:149], v[26:27], s[14:15], v[58:59] op_sel_hi:[1,0,0]
	v_pk_fma_f32 v[134:135], v[24:25], s[14:15], v[58:59] op_sel_hi:[1,0,0]
	v_pk_fma_f32 v[136:137], v[22:23], s[14:15], v[58:59] op_sel_hi:[1,0,0]
	v_pk_fma_f32 v[138:139], v[20:21], s[14:15], v[58:59] op_sel_hi:[1,0,0]
	s_waitcnt vmcnt(3)
	ds_write_b128 v164, v[218:221] offset:16384
	s_waitcnt vmcnt(2)
	ds_write_b128 v165, v[222:225] offset:16384
	s_waitcnt vmcnt(1)
	ds_write_b128 v162, v[226:229] offset:49152
	s_waitcnt vmcnt(0)
	ds_write_b128 v163, v[230:233] offset:49152
	v_lshl_add_u64 v[132:133], s[12:13], 0, v[16:17]
	v_mov_b64_e32 v[62:63], v[14:15]
	v_mov_b64_e32 v[46:47], v[14:15]
	v_mov_b64_e32 v[30:31], v[14:15]
	s_mov_b32 s68, -1
	v_mov_b64_e32 v[60:61], v[12:13]
	v_mov_b64_e32 v[58:59], v[10:11]
	v_mov_b64_e32 v[56:57], v[8:9]
	v_mov_b64_e32 v[54:55], v[6:7]
	v_mov_b64_e32 v[52:53], v[4:5]
	v_mov_b64_e32 v[50:51], v[2:3]
	v_mov_b64_e32 v[48:49], v[0:1]
	v_mov_b64_e32 v[44:45], v[12:13]
	v_mov_b64_e32 v[42:43], v[10:11]
	v_mov_b64_e32 v[40:41], v[8:9]
	v_mov_b64_e32 v[38:39], v[6:7]
	v_mov_b64_e32 v[36:37], v[4:5]
	v_mov_b64_e32 v[34:35], v[2:3]
	v_mov_b64_e32 v[32:33], v[0:1]
	v_mov_b64_e32 v[28:29], v[12:13]
	v_mov_b64_e32 v[26:27], v[10:11]
	v_mov_b64_e32 v[24:25], v[8:9]
	v_mov_b64_e32 v[22:23], v[6:7]
	v_mov_b64_e32 v[20:21], v[4:5]
	v_mov_b64_e32 v[18:19], v[2:3]
	v_mov_b64_e32 v[16:17], v[0:1]
	s_waitcnt lgkmcnt(0)
	s_barrier
	v_readfirstlane_b32 s28, v132
	v_readfirstlane_b32 s29, v133
	s_nop 1
	v_subrev_u32_e32 v132, s28, v132
	v_add_u32_e32 v133, 0x4000, v132
	s_sub_u32 s30, s28, 0x120c000
	s_subb_u32 s31, s29, 0
	s_sub_u32 s28, s28, 0xc000
	s_subb_u32 s29, s29, 0
